# grid barriers: each workgroup issues its L1 invalidate right after its arrival (before polling) instead of after the release; leader overlaps it with the top-level atomic
# speedup vs baseline: 1.0311x; 1.0128x over previous
.Lgb0_noclr:
	v_add_u32_e32 v253, 0x1000, v251
	v_add_u32_e32 v255, 0x2000, v251
	s_nop 0
	global_atomic_add v254, v253, v252, s[4:5] offset:1024 sc0
	s_waitcnt vmcnt(0)
	v_readfirstlane_b32 s10, v254
	s_nop 1
	s_add_u32 s10, s10, 1
	s_cmp_eq_u32 s10, s8
	s_cbranch_scc0 .Lgb0_follower
	buffer_wbl2 sc1
	s_waitcnt vmcnt(0)
	buffer_inv sc1
	global_atomic_add v254, v0, v252, s[4:5] sc0
	s_waitcnt vmcnt(0)
	v_readfirstlane_b32 s10, v254
	s_nop 1
	s_add_u32 s10, s10, 1
	s_cmp_eq_u32 s10, s9
	s_cbranch_scc0 .Lgb0_topwait
	global_atomic_add v0, v252, s[4:5] offset:256
	s_branch .Lgb0_topdone

.Lgb0_topdone:
	global_atomic_add v255, v252, s[4:5] offset:1024
	s_branch .Lgb0_done
.Lgb0_follower:
	buffer_inv sc1
	s_movk_i32 s11, 0x4000
.Lgb0_fspin:
	global_load_dword v254, v255, s[4:5] offset:1024 sc1
	s_waitcnt vmcnt(0)
	v_readfirstlane_b32 s10, v254
	s_nop 1
	s_cmp_lg_u32 s10, 0
	s_cbranch_scc1 .Lgb0_fdone
	s_sleep 1
	s_sub_u32 s11, s11, 1
	s_cmp_lg_u32 s11, 0
	s_cbranch_scc1 .Lgb0_fspin
.Lgb0_fdone:
	s_waitcnt vmcnt(0)
.Lgb0_done:
	s_waitcnt lgkmcnt(0)
	v_readlane_b32 s10, v249, 10
	v_readlane_b32 s11, v249, 11
	v_readlane_b32 s12, v249, 12
	v_readlane_b32 s13, v249, 13
	s_nop 4

.LBB0_127:
	s_waitcnt vmcnt(0)
	s_barrier
	s_mov_b64 s[2:3], exec
	v_readlane_b32 s4, v248, 7
	v_readlane_b32 s5, v248, 8
	s_and_b64 s[4:5], s[2:3], s[4:5]
	s_mov_b64 exec, s[4:5]
	s_cbranch_execz .LBB0_179
	v_readlane_b32 s4, v248, 4
	v_readlane_b32 s5, v248, 5
	v_readlane_b32 s8, v248, 6
	v_readlane_b32 s9, v249, 14
	v_readlane_b32 s10, v249, 15
	v_mov_b32_e32 v1, 1
	v_mov_b32_e32 v3, 0x3400
	s_nop 1
	s_lshl_b32 s8, s8, 8
	s_mul_i32 s9, s9, 2
	s_mul_i32 s10, s10, 2
	v_mov_b32_e32 v0, s8
	v_add_u32_e32 v2, 0x1000, v0
	v_add_u32_e32 v4, 0x2000, v0
	s_nop 1
	global_atomic_add v5, v2, v1, s[4:5] offset:1024 sc0
	s_waitcnt vmcnt(0)
	v_readfirstlane_b32 s11, v5
	s_nop 1
	s_add_u32 s11, s11, 1
	s_cmp_eq_u32 s11, s9
	s_cbranch_scc0 .Lhb1_follower
	buffer_wbl2 sc1
	s_waitcnt vmcnt(0)
	buffer_inv sc1
	global_atomic_add v5, v3, v1, s[4:5] sc0
	s_waitcnt vmcnt(0)
	v_readfirstlane_b32 s11, v5
	s_nop 1
	s_add_u32 s11, s11, 1
	s_cmp_ge_u32 s11, s10
	s_cbranch_scc1 .Lhb1_topdone
	s_movk_i32 s12, 0x4000

.Lhb1_topdone:
	global_atomic_add v4, v1, s[4:5] offset:1024
	s_branch .Lhb1_done
.Lhb1_follower:
	buffer_inv sc1
	s_movk_i32 s12, 0x4000
.Lhb1_fspin:
	global_load_dword v5, v4, s[4:5] offset:1024 sc1
	s_waitcnt vmcnt(0)
	v_readfirstlane_b32 s11, v5
	s_nop 1
	s_cmp_gt_u32 s11, 1
	s_cbranch_scc1 .Lhb1_fdone
	s_sleep 1
	s_sub_u32 s12, s12, 1
	s_cmp_lg_u32 s12, 0
	s_cbranch_scc1 .Lhb1_fspin
.Lhb1_fdone:
	s_waitcnt vmcnt(0)
.Lhb1_done:
.LBB0_179:
	s_or_b64 exec, exec, s[2:3]
	s_waitcnt lgkmcnt(0)
	v_mov_b32_e32 v0, v192
	v_mov_b32_e32 v8, v192
	s_cmpk_lt_i32 s96, 0x6b4
	s_barrier
	s_cselect_b64 s[2:3], -1, 0
	s_cmpk_gt_i32 s96, 0x6b3
	v_readfirstlane_b32 s6, v8
	s_cbranch_scc1 .LBB0_185
	s_ashr_i32 s4, s96, 31
	s_lshr_b32 s4, s4, 29
	s_add_i32 s7, s96, s4
	s_and_b32 s4, s7, -8
	s_sub_i32 s8, s96, s4
	s_cmp_gt_i32 s8, 3
	s_cbranch_scc0 .LBB0_182
	s_mul_i32 s4, s8, 0xd6
	s_add_i32 s9, s4, 4
	s_cbranch_execz .LBB0_183
	s_branch .LBB0_184

.LBB0_309:
	s_waitcnt vmcnt(0)
	s_barrier
	s_mov_b64 s[2:3], exec
	v_readlane_b32 s4, v248, 7
	v_readlane_b32 s5, v248, 8
	s_and_b64 s[4:5], s[2:3], s[4:5]
	s_mov_b64 exec, s[4:5]
	s_cbranch_execz .LBB0_361
	v_readlane_b32 s4, v248, 4
	v_readlane_b32 s5, v248, 5
	v_readlane_b32 s8, v248, 6
	v_readlane_b32 s9, v249, 14
	v_readlane_b32 s10, v249, 15
	v_mov_b32_e32 v1, 1
	v_mov_b32_e32 v3, 0x3400
	s_nop 1
	s_lshl_b32 s8, s8, 8
	s_mul_i32 s9, s9, 3
	s_mul_i32 s10, s10, 3
	v_mov_b32_e32 v0, s8
	v_add_u32_e32 v2, 0x1000, v0
	v_add_u32_e32 v4, 0x2000, v0
	s_nop 1
	global_atomic_add v5, v2, v1, s[4:5] offset:1024 sc0
	s_waitcnt vmcnt(0)
	v_readfirstlane_b32 s11, v5
	s_nop 1
	s_add_u32 s11, s11, 1
	s_cmp_eq_u32 s11, s9
	s_cbranch_scc0 .Lhb2_follower
	buffer_wbl2 sc1
	s_waitcnt vmcnt(0)
	buffer_inv sc1
	global_atomic_add v5, v3, v1, s[4:5] sc0
	s_waitcnt vmcnt(0)
	v_readfirstlane_b32 s11, v5
	s_nop 1
	s_add_u32 s11, s11, 1
	s_cmp_ge_u32 s11, s10
	s_cbranch_scc1 .Lhb2_topdone
	s_movk_i32 s12, 0x4000

.Lhb2_fspin:
	global_load_dword v5, v4, s[4:5] offset:1024 sc1
	s_waitcnt vmcnt(0)
	v_readfirstlane_b32 s11, v5
	s_nop 1
	s_cmp_gt_u32 s11, 2
	s_cbranch_scc1 .Lhb2_fdone
	s_sleep 1
	s_sub_u32 s12, s12, 1
	s_cmp_lg_u32 s12, 0
	s_cbranch_scc1 .Lhb2_fspin
.Lhb2_fdone:
	s_waitcnt vmcnt(0)
.Lhb2_done:
.LBB0_361:
	s_or_b64 exec, exec, s[2:3]
	v_mov_b32_e32 v96, v192
	s_waitcnt lgkmcnt(0)
	s_barrier
	s_load_dwordx2 s[68:69], s[0:1], 0xf0
	v_readlane_b32 s2, v248, 1
	v_readfirstlane_b32 s51, v96
	s_waitcnt lgkmcnt(0)
	s_add_u32 s62, s68, 0x8b00000
	v_add_u32_e32 v6, s2, v96
	s_mov_b32 s2, 0x20000
	s_addc_u32 s63, s69, 0
	v_cmp_gt_i32_e32 vcc, s2, v6
	s_and_saveexec_b64 s[2:3], vcc
	s_cbranch_execz .LBB0_368
	v_and_b32_e32 v4, 0x1ff, v96
	s_movk_i32 s4, 0xff
	v_cmp_lt_u32_e64 s[6:7], s4, v4
	s_load_dwordx2 s[4:5], s[0:1], 0xe8
	v_mov_b32_e32 v1, 0
	v_lshlrev_b32_e32 v0, 1, v4
	s_lshl_b32 s12, s92, 9
	v_lshl_add_u64 v[2:3], s[62:63], 0, v[0:1]
	s_mov_b64 s[8:9], 0
	s_movk_i32 s13, 0x1f80
	s_mov_b32 s14, 0x1ffff
	v_lshlrev_b32_e32 v0, 2, v4
	s_branch .LBB0_364

.LBB0_616:
	s_waitcnt vmcnt(0)
	s_barrier
	s_mov_b64 s[2:3], exec
	v_readlane_b32 s4, v248, 7
	v_readlane_b32 s5, v248, 8
	s_and_b64 s[4:5], s[2:3], s[4:5]
	s_mov_b64 exec, s[4:5]
	s_cbranch_execz .LBB0_668
	v_readlane_b32 s4, v248, 4
	v_readlane_b32 s5, v248, 5
	v_readlane_b32 s8, v248, 6
	v_readlane_b32 s9, v249, 14
	v_readlane_b32 s10, v249, 15
	v_mov_b32_e32 v1, 1
	v_mov_b32_e32 v3, 0x3400
	s_nop 1
	s_lshl_b32 s8, s8, 8
	s_mul_i32 s9, s9, 4
	s_mul_i32 s10, s10, 4
	v_mov_b32_e32 v0, s8
	v_add_u32_e32 v2, 0x1000, v0
	v_add_u32_e32 v4, 0x2000, v0
	s_nop 1
	global_atomic_add v5, v2, v1, s[4:5] offset:1024 sc0
	s_waitcnt vmcnt(0)
	v_readfirstlane_b32 s11, v5
	s_nop 1
	s_add_u32 s11, s11, 1
	s_cmp_eq_u32 s11, s9
	s_cbranch_scc0 .Lhb3_follower
	buffer_wbl2 sc1
	s_waitcnt vmcnt(0)
	buffer_inv sc1
	global_atomic_add v5, v3, v1, s[4:5] sc0
	s_waitcnt vmcnt(0)
	v_readfirstlane_b32 s11, v5
	s_nop 1
	s_add_u32 s11, s11, 1
	s_cmp_ge_u32 s11, s10
	s_cbranch_scc1 .Lhb3_topdone
	s_movk_i32 s12, 0x4000

.Lhb3_fspin:
	global_load_dword v5, v4, s[4:5] offset:1024 sc1
	s_waitcnt vmcnt(0)
	v_readfirstlane_b32 s11, v5
	s_nop 1
	s_cmp_gt_u32 s11, 3
	s_cbranch_scc1 .Lhb3_fdone
	s_sleep 1
	s_sub_u32 s12, s12, 1
	s_cmp_lg_u32 s12, 0
	s_cbranch_scc1 .Lhb3_fspin
.Lhb3_fdone:
	s_waitcnt vmcnt(0)
.Lhb3_done:
.LBB0_668:
	s_or_b64 exec, exec, s[2:3]
	s_cmpk_lt_i32 s96, 0x100
	s_cselect_b64 s[2:3], -1, 0
	v_mov_b32_e32 v4, v192
	v_writelane_b32 v248, s2, 35
	s_cmpk_gt_i32 s96, 0xff
	s_waitcnt lgkmcnt(0)
	s_barrier
	v_writelane_b32 v248, s3, 36
	s_cbranch_scc1 .LBB0_686
	s_load_dwordx4 s[16:19], s[0:1], 0xe8
	s_movk_i32 s2, 0x80
	v_cmp_gt_i32_e64 s[12:13], s2, v4
	v_ashrrev_i32_e32 v5, 31, v4
	v_lshlrev_b32_e32 v2, 3, v4
	s_waitcnt lgkmcnt(0)
	s_add_u32 s2, s18, 0x2750000
	s_addc_u32 s3, s19, 0
	s_add_u32 s4, s18, 0x2751000
	s_addc_u32 s5, s19, 0
	s_add_u32 s6, s16, 0x4200000
	v_lshl_add_u64 v[0:1], v[4:5], 2, s[18:19]
	s_mov_b64 s[18:19], 0x2754000
	v_cmp_eq_u32_e64 s[8:9], 0, v4
	v_cmp_gt_i32_e64 s[10:11], 64, v4
	s_addc_u32 s7, s17, 0
	v_cmp_eq_u32_e64 s[14:15], 64, v4
	v_lshlrev_b32_e32 v134, 1, v4
	v_lshl_add_u32 v135, v4, 2, 0
	v_lshl_add_u64 v[6:7], v[0:1], 0, s[18:19]
	v_mov_b32_e32 v0, 0
	v_add_u32_e32 v136, 0, v2
	v_mov_b32_e32 v137, 0x4301000
	s_mov_b32 s24, 0x10000
	s_mov_b32 s25, 0x20000
	s_mov_b32 s26, 0x30000
	s_mov_b32 s27, 0x40000
	s_mov_b32 s28, 0x50000
	s_mov_b32 s29, 0x60000
	s_mov_b32 s30, 0x70000
	s_mov_b32 s31, 0x80000
	s_mov_b32 s33, 0x90000
	s_mov_b32 s34, 0xa0000
	s_mov_b32 s35, 0xb0000
	s_mov_b32 s36, 0xc0000
	s_mov_b32 s37, 0xd0000
	s_mov_b32 s38, 0xe0000
	s_mov_b32 s39, 0xf0000
	s_mov_b32 s40, s96
	s_mov_b32 s41, s96
	s_branch .LBB0_671

.LBB0_686:
	s_waitcnt vmcnt(0)
	s_waitcnt vmcnt(63) expcnt(7) lgkmcnt(15)
	s_barrier
	s_mov_b64 s[2:3], exec
	v_readlane_b32 s4, v248, 7
	v_readlane_b32 s5, v248, 8
	s_and_b64 s[4:5], s[2:3], s[4:5]
	s_mov_b64 exec, s[4:5]
	s_cbranch_execz .LBB0_738
	v_readlane_b32 s4, v248, 4
	v_readlane_b32 s5, v248, 5
	v_readlane_b32 s8, v248, 6
	v_readlane_b32 s9, v249, 14
	v_readlane_b32 s10, v249, 15
	v_mov_b32_e32 v1, 1
	v_mov_b32_e32 v3, 0x3400
	s_nop 1
	s_lshl_b32 s8, s8, 8
	s_mul_i32 s9, s9, 5
	s_mul_i32 s10, s10, 5
	v_mov_b32_e32 v0, s8
	v_add_u32_e32 v2, 0x1000, v0
	v_add_u32_e32 v4, 0x2000, v0
	s_nop 1
	global_atomic_add v5, v2, v1, s[4:5] offset:1024 sc0
	s_waitcnt vmcnt(0)
	v_readfirstlane_b32 s11, v5
	s_nop 1
	s_add_u32 s11, s11, 1
	s_cmp_eq_u32 s11, s9
	s_cbranch_scc0 .Lhb4_follower
	buffer_wbl2 sc1
	s_waitcnt vmcnt(0)
	buffer_inv sc1
	global_atomic_add v5, v3, v1, s[4:5] sc0
	s_waitcnt vmcnt(0)
	v_readfirstlane_b32 s11, v5
	s_nop 1
	s_add_u32 s11, s11, 1
	s_cmp_ge_u32 s11, s10
	s_cbranch_scc1 .Lhb4_topdone
	s_movk_i32 s12, 0x4000

.Lhb4_fspin:
	global_load_dword v5, v4, s[4:5] offset:1024 sc1
	s_waitcnt vmcnt(0)
	v_readfirstlane_b32 s11, v5
	s_nop 1
	s_cmp_gt_u32 s11, 4
	s_cbranch_scc1 .Lhb4_fdone
	s_sleep 1
	s_sub_u32 s12, s12, 1
	s_cmp_lg_u32 s12, 0
	s_cbranch_scc1 .Lhb4_fspin
.Lhb4_fdone:
	s_waitcnt vmcnt(0)
.Lhb4_done:
.LBB0_738:
	s_or_b64 exec, exec, s[2:3]
	v_mov_b32_e32 v2, v192
	s_waitcnt lgkmcnt(0)
	s_barrier
	s_and_b64 vcc, exec, s[84:85]
	v_readfirstlane_b32 s10, v2
	s_cbranch_vccnz .LBB0_819
	s_load_dwordx4 s[88:91], s[0:1], 0xe8
	s_ashr_i32 s2, s10, 6
	v_lshlrev_b32_e32 v0, 4, v2
	v_and_b32_e32 v68, 0xf0, v0
	v_mov_b32_e32 v69, 0
	s_waitcnt lgkmcnt(0)
	s_add_u32 s4, s90, 0x4900000
	s_addc_u32 s5, s91, 0
	v_lshl_add_u64 v[0:1], s[90:91], 0, v[68:69]
	s_mov_b64 s[6:7], 0x2800000
	s_cmp_lt_u32 s10, 64
	v_lshl_add_u64 v[70:71], v[0:1], 0, s[6:7]
	s_cselect_b64 s[6:7], -1, 0
	v_writelane_b32 v248, s6, 13
	v_and_b32_e32 v3, 63, v2
	v_cmp_gt_u32_e64 s[8:9], 2, v3
	v_writelane_b32 v248, s7, 14
	s_add_u32 s6, s90, 0x26a0000
	s_addc_u32 s7, s91, 0
	v_writelane_b32 v248, s6, 29
	v_lshlrev_b32_e32 v0, 3, v3
	s_add_i32 s3, 0, 0x22200
	v_writelane_b32 v248, s7, 30
	v_writelane_b32 v248, s8, 18
	v_add_u32_e32 v103, s3, v0
	s_add_i32 s3, 0, 0x22400
	v_writelane_b32 v248, s9, 19
	v_cmp_gt_u32_e64 s[8:9], 4, v3
	v_add_u32_e32 v104, s3, v0
	s_add_i32 s3, 0, 0x22600
	v_writelane_b32 v248, s8, 20
	v_add_u32_e32 v105, s3, v0
	s_add_i32 s3, 0, 0x22800
	v_writelane_b32 v248, s9, 21
	v_cmp_gt_u32_e64 s[8:9], 8, v3
	s_add_i32 s11, 0, 0x22000
	v_add_u32_e32 v106, s3, v0
	v_writelane_b32 v248, s8, 31
	s_movk_i32 s3, 0x80
	v_lshlrev_b32_e32 v101, 1, v3
	v_writelane_b32 v248, s9, 32
	v_cmp_gt_u32_e64 s[8:9], 16, v3
	v_cmp_eq_u32_e64 s[6:7], 0, v3
	v_cmp_gt_u32_e64 s[16:17], 32, v3
	v_writelane_b32 v248, s8, 33
	v_cmp_gt_i32_e64 s[12:13], s3, v2
	s_add_u32 s3, s90, 0x2751000
	v_writelane_b32 v248, s9, 34
	v_ashrrev_i32_e32 v3, 31, v2
	v_add_u32_e32 v17, 0x200, v2
	s_waitcnt vmcnt(0)
	v_add_u32_e32 v18, 0x400, v2
	v_add_u32_e32 v19, 0x600, v2
	v_add_u32_e32 v102, s11, v0
	v_writelane_b32 v248, s3, 15
	s_addc_u32 s3, s91, 0
	v_lshl_add_u64 v[0:1], v[2:3], 2, s[90:91]
	s_mov_b64 s[8:9], 0x2754000
	v_ashrrev_i32_e32 v95, 4, v2
	v_ashrrev_i32_e32 v98, 4, v17
	v_ashrrev_i32_e32 v99, 4, v18
	v_ashrrev_i32_e32 v100, 4, v19
	v_writelane_b32 v248, s3, 16
	v_lshl_add_u64 v[90:91], v[0:1], 0, s[8:9]
	s_movk_i32 s3, 0x110
	s_and_b32 s20, s2, 3
	s_ashr_i32 s8, s10, 8
	v_lshl_add_u64 v[72:73], s[88:89], 0, v[68:69]
	s_add_i32 s14, 0, 0x22a00
	s_add_i32 s15, 0, 0x22c00
	s_add_i32 s18, 0, 0x22e00
	s_add_i32 s19, 0, 0x23200
	v_add_u32_e32 v0, 0, v68
	v_mul_lo_u32 v112, v95, s3
	v_mul_lo_u32 v114, v98, s3
	v_mul_lo_u32 v116, v99, s3
	v_mul_lo_u32 v118, v100, s3
	s_add_i32 s88, 0, 0x11000
	v_add_u32_e32 v20, 0x800, v2
	s_lshl_b32 s9, s8, 1
	s_lshl_b32 s21, s20, 5
	v_lshlrev_b32_e32 v4, 2, v2
	v_add_u32_e32 v113, v0, v112
	v_add_u32_e32 v115, v0, v114
	v_add_u32_e32 v117, v0, v116
	v_add_u32_e32 v119, v0, v118
	v_lshrrev_b32_e32 v0, 4, v20
	v_add_u32_e32 v21, 0xa00, v2
	s_cmp_ge_i32 s9, s20
	v_add_u32_e32 v107, s11, v4
	v_add_u32_e32 v108, s14, v4
	v_add_u32_e32 v109, s15, v4
	v_add_u32_e32 v110, s18, v4
	v_add_u32_e32 v111, s19, v4
	v_mul_lo_u32 v4, v0, s3
	v_lshrrev_b32_e32 v0, 4, v21
	v_add_u32_e32 v22, 0xc00, v2
	s_cselect_b64 s[22:23], -1, 0
	v_mul_lo_u32 v5, v0, s3
	v_lshrrev_b32_e32 v0, 4, v22
	v_add_u32_e32 v23, 0xe00, v2
	v_writelane_b32 v248, s22, 22
	v_mul_lo_u32 v6, v0, s3
	v_lshrrev_b32_e32 v0, 4, v23
	v_writelane_b32 v248, s23, 23
	s_or_b32 s22, s9, 1
	v_mul_lo_u32 v7, v0, s3
	v_and_b32_e32 v8, 31, v2
	v_bfe_u32 v0, v2, 5, 1
	s_cmp_ge_i32 s22, s20
	v_lshlrev_b32_e32 v24, 3, v0
	v_lshlrev_b32_e32 v9, 4, v0
	v_lshl_or_b32 v1, s8, 6, v8
	s_cselect_b64 s[8:9], -1, 0
	v_lshl_or_b32 v0, v0, 2, s21
	s_lshl_b32 s33, s20, 6
	s_add_i32 s20, s33, 0
	v_or_b32_e32 v13, 2, v0
	v_or_b32_e32 v15, 3, v0
	v_or_b32_e32 v16, 8, v0
	v_or_b32_e32 v25, 9, v0
	v_or_b32_e32 v26, 10, v0
	v_or_b32_e32 v27, 11, v0
	v_or_b32_e32 v28, 16, v0
	v_or_b32_e32 v29, 17, v0
	v_or_b32_e32 v30, 18, v0
	v_or_b32_e32 v31, 19, v0
	v_or_b32_e32 v32, 24, v0
	v_or_b32_e32 v33, 25, v0
	v_or_b32_e32 v34, 26, v0
	v_or_b32_e32 v35, 27, v0
	v_or_b32_e32 v14, s21, v8
	v_mul_lo_u32 v123, v1, s3
	v_lshl_or_b32 v3, s22, 5, v8
	v_add_u32_e32 v124, s20, v24
	v_lshl_add_u32 v125, v1, 2, s14
	v_cmp_le_i32_e64 s[20:21], v0, v1
	v_cmp_lt_i32_e64 s[22:23], v0, v1
	v_cmp_le_i32_e64 s[24:25], v13, v1
	v_cmp_le_i32_e64 s[26:27], v15, v1
	v_cmp_le_i32_e64 s[28:29], v16, v1
	v_cmp_le_i32_e64 s[30:31], v25, v1
	v_cmp_le_i32_e64 s[34:35], v26, v1
	v_cmp_le_i32_e64 s[36:37], v27, v1
	v_cmp_le_i32_e64 s[38:39], v28, v1
	v_cmp_le_i32_e64 s[40:41], v29, v1
	v_cmp_le_i32_e64 s[42:43], v30, v1
	v_cmp_le_i32_e64 s[44:45], v31, v1
	v_cmp_le_i32_e64 s[46:47], v32, v1
	v_cmp_le_i32_e64 s[48:49], v33, v1
	v_cmp_le_i32_e64 s[50:51], v34, v1
	v_cmp_le_i32_e64 s[52:53], v35, v1
	v_or_b32_e32 v1, 32, v1
	v_lshl_add_u32 v126, v0, 2, s11
	v_lshl_add_u32 v127, v13, 2, s11
	v_lshl_add_u32 v128, v15, 2, s11
	v_lshl_add_u32 v129, v16, 2, s11
	v_lshl_add_u32 v130, v25, 2, s11
	v_lshl_add_u32 v131, v26, 2, s11
	v_lshl_add_u32 v132, v27, 2, s11
	v_lshl_add_u32 v133, v28, 2, s11
	v_lshl_add_u32 v134, v29, 2, s11
	v_lshl_add_u32 v135, v30, 2, s11
	v_lshl_add_u32 v136, v31, 2, s11
	v_lshl_add_u32 v137, v32, 2, s11
	v_lshl_add_u32 v138, v33, 2, s11
	v_lshl_add_u32 v139, v34, 2, s11
	v_lshl_add_u32 v140, v35, 2, s11
	v_cmp_le_i32_e64 s[54:55], v0, v1
	v_cmp_lt_i32_e64 s[56:57], v0, v1
	v_lshrrev_b32_e32 v0, 2, v2
	s_movk_i32 s11, 0x88
	v_mul_lo_u32 v10, v3, s3
	v_lshl_add_u32 v141, v1, 2, s14
	v_mul_lo_u32 v3, v1, s3
	v_cmp_le_i32_e64 s[58:59], v13, v1
	v_cmp_le_i32_e64 s[60:61], v15, v1
	v_cmp_le_i32_e64 s[62:63], v16, v1
	v_cmp_le_i32_e64 s[64:65], v25, v1
	v_cmp_le_i32_e64 s[66:67], v26, v1
	v_cmp_le_i32_e64 s[68:69], v27, v1
	v_cmp_le_i32_e64 s[70:71], v28, v1
	v_cmp_le_i32_e64 s[72:73], v29, v1
	v_cmp_le_i32_e64 s[74:75], v30, v1
	v_cmp_le_i32_e64 s[76:77], v31, v1
	v_cmp_le_i32_e64 s[78:79], v32, v1
	v_cmp_le_i32_e64 s[80:81], v33, v1
	v_cmp_le_i32_e64 s[82:83], v34, v1
	v_cmp_le_i32_e64 s[84:85], v35, v1
	v_and_b32_e32 v1, 3, v2
	v_mul_lo_u32 v0, v0, s11
	v_mbcnt_hi_u32_b32 v15, -1, v193
	v_lshl_add_u32 v0, v1, 5, v0
	v_and_b32_e32 v16, 64, v15
	v_lshl_add_u32 v143, v0, 1, 0
	v_xor_b32_e32 v0, 1, v15
	v_add_u32_e32 v25, 64, v16
	v_cmp_lt_i32_e32 vcc, v0, v25
	v_add_u32_e32 v121, 0, v9
	s_add_i32 s11, 0, 0x23000
	v_cndmask_b32_e32 v0, v15, v0, vcc
	v_lshlrev_b32_e32 v144, 2, v0
	v_xor_b32_e32 v0, 2, v15
	v_lshlrev_b32_e32 v26, 2, v14
	v_mul_u32_u24_e32 v11, 0x110, v14
	v_mad_u32_u24 v122, v14, s3, v121
	v_cmp_lt_i32_e32 vcc, v0, v25
	v_add_u32_e32 v151, s15, v26
	v_add_u32_e32 v175, s11, v26
	v_xor_b32_e32 v26, 32, v15
	v_lshlrev_b32_e32 v177, 3, v14
	v_mul_u32_u24_e32 v14, 0x210, v14
	v_cndmask_b32_e32 v0, v15, v0, vcc
	v_cmp_lt_i32_e32 vcc, v26, v25
	v_add3_u32 v14, 0, v14, v24
	v_add_u32_e32 v24, -1, v15
	v_cndmask_b32_e32 v25, v15, v26, vcc
	v_cmp_lt_i32_e32 vcc, v24, v16
	v_lshlrev_b32_e32 v145, 2, v0
	v_and_b32_e32 v0, -4, v2
	s_lshl_b32 s14, s2, 5
	v_cndmask_b32_e32 v24, v24, v15, vcc
	v_add_u32_e32 v147, s18, v0
	s_and_b32 s18, s14, 0xfffff80
	v_lshlrev_b32_e32 v187, 2, v24
	v_add_u32_e32 v24, -2, v15
	v_add_u32_e32 v146, s15, v0
	v_add_u32_e32 v148, s11, v0
	v_or_b32_e32 v0, s18, v8
	v_cmp_lt_i32_e32 vcc, v24, v16
	v_mul_lo_u32 v13, v0, s3
	v_or_b32_e32 v0, s14, v8
	v_cndmask_b32_e32 v24, v24, v15, vcc
	v_or_b32_e32 v0, 0x60, v0
	v_lshlrev_b32_e32 v188, 2, v24
	v_add_u32_e32 v24, -4, v15
	v_mul_lo_u32 v150, v0, s3
	v_and_b32_e32 v0, 1, v2
	v_cmp_lt_i32_e32 vcc, v24, v16
	v_lshl_or_b32 v27, s2, 2, v0
	s_movk_i32 s14, 0x880
	v_cndmask_b32_e32 v24, v24, v15, vcc
	v_lshlrev_b32_e32 v0, 3, v27
	v_mul_lo_u32 v27, v27, s14
	s_and_b32 s14, s10, 0xffffff00
	v_lshlrev_b32_e32 v189, 2, v24
	v_add_u32_e32 v24, -8, v15
	s_lshl_b32 s10, s14, 2
	v_cmp_lt_i32_e32 vcc, v24, v16
	v_writelane_b32 v248, s8, 24
	s_add_i32 s10, s10, 0
	v_cndmask_b32_e32 v24, v24, v15, vcc
	v_writelane_b32 v248, s9, 25
	v_bfe_u32 v152, v2, 1, 5
	s_add_i32 s8, s10, 0x23400
	v_lshlrev_b32_e32 v190, 2, v24
	v_add_u32_e32 v24, -16, v15
	v_and_b32_e32 v28, 62, v2
	v_or_b32_e32 v158, 32, v152
	v_or_b32_e32 v161, 64, v152
	v_or_b32_e32 v164, 0x60, v152
	v_writelane_b32 v248, s8, 28
	s_add_u32 s8, s90, 0x9b80000
	v_cmp_lt_i32_e32 vcc, v24, v16
	v_add_u32_e32 v29, s88, v28
	v_lshlrev_b32_e32 v31, 1, v158
	v_lshlrev_b32_e32 v32, 1, v161
	v_lshlrev_b32_e32 v33, 1, v164
	s_addc_u32 s9, s91, 0
	s_load_dwordx2 s[10:11], s[0:1], 0x70
	v_cndmask_b32_e32 v24, v24, v15, vcc
	s_lshr_b32 s2, s2, 2
	v_lshlrev_b32_e32 v12, 3, v2
	v_add_u32_e32 v153, v29, v27
	v_add_u32_e32 v30, s88, v27
	v_add3_u32 v160, s88, v31, v27
	v_add3_u32 v163, s88, v32, v27
	v_add3_u32 v166, s88, v33, v27
	v_or_b32_e32 v27, 16, v0
	v_lshlrev_b32_e32 v191, 2, v24
	v_subrev_u32_e32 v24, 32, v15
	v_add3_u32 v11, v11, v9, 0
	s_mul_i32 s2, s2, 0x8800
	v_and_b32_e32 v74, 0xffffff80, v12
	v_mul_lo_u32 v27, v27, s3
	s_movk_i32 s15, 0x210
	v_and_b32_e32 v178, 0xf8, v12
	v_ashrrev_i32_e32 v179, 5, v2
	v_ashrrev_i32_e32 v180, 5, v17
	v_ashrrev_i32_e32 v181, 5, v18
	v_ashrrev_i32_e32 v182, 5, v19
	v_ashrrev_i32_e32 v183, 5, v20
	v_ashrrev_i32_e32 v184, 5, v21
	v_ashrrev_i32_e32 v185, 5, v22
	v_ashrrev_i32_e32 v186, 5, v23
	v_cmp_lt_i32_e32 vcc, v24, v16
	v_add_u32_e32 v195, 0x8800, v11
	v_mov_b32_e32 v11, s2
	v_add_u32_e32 v76, 0x1000, v74
	v_add_u32_e32 v78, 0x2000, v74
	v_add_u32_e32 v80, 0x3000, v74
	v_add_u32_e32 v82, 0x4000, v74
	v_add_u32_e32 v84, 0x5000, v74
	v_add_u32_e32 v86, 0x6000, v74
	v_add_u32_e32 v88, 0x7000, v74
	v_add_u32_e32 v120, s88, v68
	v_lshl_add_u32 v142, v1, 7, s19
	v_cmp_eq_u32_e64 s[86:87], 0, v1
	v_add_u32_e32 v149, s88, v9
	v_ashrrev_i32_e32 v1, 31, v0
	v_add_u32_e32 v167, v29, v27
	v_add_u32_e32 v27, s88, v27
	v_lshl_add_u32 v12, v178, 1, 0
	v_mul_lo_u32 v2, v179, s15
	v_mul_lo_u32 v17, v180, s15
	v_mul_lo_u32 v18, v181, s15
	v_mul_lo_u32 v19, v182, s15
	v_mul_lo_u32 v20, v183, s15
	v_mul_lo_u32 v21, v184, s15
	v_mul_lo_u32 v22, v185, s15
	v_mul_lo_u32 v23, v186, s15
	v_cndmask_b32_e32 v15, v24, v15, vcc
	v_mad_u32_u24 v8, v8, s3, v11
	v_ashrrev_i32_e32 v75, 31, v74
	v_ashrrev_i32_e32 v77, 31, v76
	v_ashrrev_i32_e32 v79, 31, v78
	v_ashrrev_i32_e32 v81, 31, v80
	v_ashrrev_i32_e32 v83, 31, v82
	v_ashrrev_i32_e32 v85, 31, v84
	v_ashrrev_i32_e32 v87, 31, v86
	v_ashrrev_i32_e32 v89, 31, v88
	s_mov_b32 s95, 0
	v_add_u32_e32 v154, v30, v28
	v_add_u32_e32 v155, 0x220, v153
	v_add_u32_e32 v156, 0x440, v153
	v_add_u32_e32 v157, 0x660, v153
	v_add_u32_e32 v159, v30, v31
	v_add_u32_e32 v162, v30, v32
	v_add_u32_e32 v165, v30, v33
	v_add_u32_e32 v168, v27, v28
	v_add_u32_e32 v169, 0x1320, v153
	v_add_u32_e32 v170, 0x1540, v153
	v_add_u32_e32 v171, 0x1760, v153
	v_add_u32_e32 v172, v27, v31
	v_add_u32_e32 v173, v27, v32
	v_add_u32_e32 v174, v27, v33
	v_lshlrev_b32_e32 v176, 2, v25
	v_writelane_b32 v248, s8, 26
	v_lshlrev_b32_e32 v194, 2, v15
	s_add_i32 s33, s33, 64
	v_add3_u32 v196, v150, v9, 0
	v_add3_u32 v197, v8, v9, 0
	v_add_u32_e32 v198, v120, v4
	v_add_u32_e32 v199, v120, v5
	v_add_u32_e32 v200, v120, v6
	v_add_u32_e32 v201, v120, v7
	v_add_u32_e32 v202, v121, v10
	v_add_u32_e32 v203, v149, v13
	v_lshlrev_b64 v[92:93], 1, v[0:1]
	v_mov_b32_e32 v204, 0x260
	v_add_u32_e32 v205, s14, v14
	v_add_u32_e32 v206, v12, v2
	v_add_u32_e32 v207, v12, v17
	v_add_u32_e32 v208, v12, v18
	v_add_u32_e32 v209, v12, v19
	v_add_u32_e32 v210, v12, v20
	v_add_u32_e32 v211, v12, v21
	v_add_u32_e32 v212, v12, v22
	v_add_u32_e32 v213, v12, v23
	v_mov_b32_e32 v94, 0x3ecc95a3
	v_mov_b32_e32 v214, 0x7f800000
	v_mov_b32_e32 v215, 0x7fc00000
	v_mov_b32_e32 v216, 0xff800000
	v_add_u32_e32 v217, v124, v3
	s_mov_b32 s2, s96
	v_writelane_b32 v248, s9, 27
	s_branch .LBB0_741

.LBB0_819:
	s_waitcnt vmcnt(0)
	s_barrier
	s_mov_b64 s[2:3], exec
	v_readlane_b32 s4, v248, 7
	v_readlane_b32 s5, v248, 8
	s_and_b64 s[4:5], s[2:3], s[4:5]
	s_mov_b64 exec, s[4:5]
	s_cbranch_execz .LBB0_871
	v_readlane_b32 s4, v248, 4
	v_readlane_b32 s5, v248, 5
	v_readlane_b32 s8, v248, 6
	v_readlane_b32 s9, v249, 14
	v_readlane_b32 s10, v249, 15
	v_mov_b32_e32 v1, 1
	v_mov_b32_e32 v3, 0x3400
	s_nop 1
	s_lshl_b32 s8, s8, 8
	s_mul_i32 s9, s9, 6
	s_mul_i32 s10, s10, 6
	v_mov_b32_e32 v0, s8
	v_add_u32_e32 v2, 0x1000, v0
	v_add_u32_e32 v4, 0x2000, v0
	s_nop 1
	global_atomic_add v5, v2, v1, s[4:5] offset:1024 sc0
	s_waitcnt vmcnt(0)
	v_readfirstlane_b32 s11, v5
	s_nop 1
	s_add_u32 s11, s11, 1
	s_cmp_eq_u32 s11, s9
	s_cbranch_scc0 .Lhb5_follower
	buffer_wbl2 sc1
	s_waitcnt vmcnt(0)
	buffer_inv sc1
	global_atomic_add v5, v3, v1, s[4:5] sc0
	s_waitcnt vmcnt(0)
	v_readfirstlane_b32 s11, v5
	s_nop 1
	s_add_u32 s11, s11, 1
	s_cmp_ge_u32 s11, s10
	s_cbranch_scc1 .Lhb5_topdone
	s_movk_i32 s12, 0x4000

.Lhb5_fspin:
	global_load_dword v5, v4, s[4:5] offset:1024 sc1
	s_waitcnt vmcnt(0)
	v_readfirstlane_b32 s11, v5
	s_nop 1
	s_cmp_gt_u32 s11, 5
	s_cbranch_scc1 .Lhb5_fdone
	s_sleep 1
	s_sub_u32 s12, s12, 1
	s_cmp_lg_u32 s12, 0
	s_cbranch_scc1 .Lhb5_fspin
.Lhb5_fdone:
	s_waitcnt vmcnt(0)
.Lhb5_done:
.LBB0_871:
	s_or_b64 exec, exec, s[2:3]
	s_waitcnt lgkmcnt(0)
	v_mov_b32_e32 v0, v192
	s_barrier
	s_load_dwordx2 s[10:11], s[0:1], 0xf0
	v_readlane_b32 s8, v248, 35
	v_readlane_b32 s9, v248, 36
	v_mov_b32_e32 v8, v192
	s_waitcnt lgkmcnt(0)
	s_add_u32 s2, s10, 0xbc80000
	s_addc_u32 s3, s11, 0
	s_add_u32 s4, s10, 0x2800000
	v_cndmask_b32_e64 v0, 0, 1, s[8:9]
	s_addc_u32 s5, s11, 0
	v_cmp_ne_u32_e64 s[6:7], 1, v0
	s_andn2_b64 vcc, exec, s[8:9]
	v_readfirstlane_b32 s18, v8
	s_cbranch_vccnz .LBB0_897
	s_ashr_i32 s33, s96, 31
	s_lshr_b32 s8, s33, 29
	s_add_i32 s13, s96, s8
	s_and_b32 s8, s13, -8
	s_sub_i32 s14, s96, s8
	s_cmp_gt_i32 s14, -1
	s_cbranch_scc0 .LBB0_874
	s_lshl_b32 s12, s14, 5
	s_cbranch_execz .LBB0_875
	s_branch .LBB0_876

.LBB0_904:
	s_waitcnt vmcnt(0)
	s_barrier
	s_mov_b64 s[2:3], exec
	v_readlane_b32 s4, v248, 7
	v_readlane_b32 s5, v248, 8
	s_and_b64 s[4:5], s[2:3], s[4:5]
	s_mov_b64 exec, s[4:5]
	s_cbranch_execz .LBB0_956
	v_readlane_b32 s4, v248, 4
	v_readlane_b32 s5, v248, 5
	v_readlane_b32 s8, v248, 6
	v_readlane_b32 s9, v249, 14
	v_readlane_b32 s10, v249, 15
	v_mov_b32_e32 v1, 1
	v_mov_b32_e32 v3, 0x3400
	s_nop 1
	s_lshl_b32 s8, s8, 8
	s_mul_i32 s9, s9, 7
	s_mul_i32 s10, s10, 7
	v_mov_b32_e32 v0, s8
	v_add_u32_e32 v2, 0x1000, v0
	v_add_u32_e32 v4, 0x2000, v0
	s_nop 1
	global_atomic_add v5, v2, v1, s[4:5] offset:1024 sc0
	s_waitcnt vmcnt(0)
	v_readfirstlane_b32 s11, v5
	s_nop 1
	s_add_u32 s11, s11, 1
	s_cmp_eq_u32 s11, s9
	s_cbranch_scc0 .Lhb6_follower
	buffer_wbl2 sc1
	s_waitcnt vmcnt(0)
	buffer_inv sc1
	global_atomic_add v5, v3, v1, s[4:5] sc0
	s_waitcnt vmcnt(0)
	v_readfirstlane_b32 s11, v5
	s_nop 1
	s_add_u32 s11, s11, 1
	s_cmp_ge_u32 s11, s10
	s_cbranch_scc1 .Lhb6_topdone
	s_movk_i32 s12, 0x4000

.Lhb6_fspin:
	global_load_dword v5, v4, s[4:5] offset:1024 sc1
	s_waitcnt vmcnt(0)
	v_readfirstlane_b32 s11, v5
	s_nop 1
	s_cmp_gt_u32 s11, 6
	s_cbranch_scc1 .Lhb6_fdone
	s_sleep 1
	s_sub_u32 s12, s12, 1
	s_cmp_lg_u32 s12, 0
	s_cbranch_scc1 .Lhb6_fspin
.Lhb6_fdone:
	s_waitcnt vmcnt(0)
.Lhb6_done:
.LBB0_956:
	s_or_b64 exec, exec, s[2:3]
	s_waitcnt lgkmcnt(0)
	v_mov_b32_e32 v0, v192
	s_barrier
	s_load_dwordx2 s[4:5], s[0:1], 0xf0
	v_mov_b32_e32 v8, v192
	s_and_b64 vcc, exec, s[6:7]
	v_readfirstlane_b32 s8, v8
	s_cbranch_vccnz .LBB0_962
	s_ashr_i32 s2, s96, 31
	s_lshr_b32 s2, s2, 29
	s_add_i32 s9, s96, s2
	s_and_b32 s2, s9, -8
	s_sub_i32 s10, s96, s2
	s_cmp_gt_i32 s10, -1
	s_cbranch_scc0 .LBB0_959
	s_lshl_b32 s11, s10, 5
	s_cbranch_execz .LBB0_960
	s_branch .LBB0_961

.LBB0_1019:
	s_waitcnt vmcnt(0)
	s_barrier
	s_mov_b64 s[2:3], exec
	v_readlane_b32 s4, v248, 7
	v_readlane_b32 s5, v248, 8
	s_and_b64 s[4:5], s[2:3], s[4:5]
	s_mov_b64 exec, s[4:5]
	s_cbranch_execz .LBB0_1071
	v_readlane_b32 s4, v248, 4
	v_readlane_b32 s5, v248, 5
	v_readlane_b32 s8, v248, 6
	v_readlane_b32 s9, v249, 14
	v_readlane_b32 s10, v249, 15
	v_mov_b32_e32 v1, 1
	v_mov_b32_e32 v3, 0x3400
	s_nop 1
	s_lshl_b32 s8, s8, 8
	s_mul_i32 s9, s9, 8
	s_mul_i32 s10, s10, 8
	v_mov_b32_e32 v0, s8
	v_add_u32_e32 v2, 0x1000, v0
	v_add_u32_e32 v4, 0x2000, v0
	s_nop 1
	global_atomic_add v5, v2, v1, s[4:5] offset:1024 sc0
	s_waitcnt vmcnt(0)
	v_readfirstlane_b32 s11, v5
	s_nop 1
	s_add_u32 s11, s11, 1
	s_cmp_eq_u32 s11, s9
	s_cbranch_scc0 .Lhb7_follower
	buffer_wbl2 sc1
	s_waitcnt vmcnt(0)
	buffer_inv sc1
	global_atomic_add v5, v3, v1, s[4:5] sc0
	s_waitcnt vmcnt(0)
	v_readfirstlane_b32 s11, v5
	s_nop 1
	s_add_u32 s11, s11, 1
	s_cmp_ge_u32 s11, s10
	s_cbranch_scc1 .Lhb7_topdone
	s_movk_i32 s12, 0x4000

.Lhb7_fspin:
	global_load_dword v5, v4, s[4:5] offset:1024 sc1
	s_waitcnt vmcnt(0)
	v_readfirstlane_b32 s11, v5
	s_nop 1
	s_cmp_gt_u32 s11, 7
	s_cbranch_scc1 .Lhb7_fdone
	s_sleep 1
	s_sub_u32 s12, s12, 1
	s_cmp_lg_u32 s12, 0
	s_cbranch_scc1 .Lhb7_fspin
.Lhb7_fdone:
	s_waitcnt vmcnt(0)
.Lhb7_done:
.LBB0_1071:
	s_or_b64 exec, exec, s[2:3]
	v_mov_b32_e32 v32, v192
	s_waitcnt lgkmcnt(0)
	s_barrier
	s_nop 0
	v_readfirstlane_b32 s2, v32
	s_ashr_i32 s10, s2, 6
	s_mul_i32 s15, s10, s92
	s_add_i32 s2, s15, s96
	s_cmpk_gt_i32 s2, 0x41ff
	s_cbranch_scc1 .LBB0_1079
	s_load_dwordx2 s[8:9], s[0:1], 0xf0
	s_load_dwordx4 s[20:23], s[0:1], 0x98
	v_lshlrev_b32_e32 v0, 2, v32
	v_and_b32_e32 v34, 0xfc, v0
	v_mov_b32_e32 v65, 0
	s_waitcnt lgkmcnt(0)
	s_add_u32 s16, s8, 0x2380000
	s_addc_u32 s17, s9, 0
	s_ashr_i32 s3, s2, 31
	s_lshl_b64 s[2:3], s[2:3], 11
	s_add_u32 s2, s8, s2
	v_lshlrev_b32_e32 v64, 1, v34
	s_addc_u32 s3, s9, s3
	v_lshl_add_u64 v[36:37], s[2:3], 0, v[64:65]
	s_mov_b64 s[4:5], 0x4900000
	v_lshlrev_b32_e32 v33, 2, v34
	v_lshl_add_u64 v[38:39], v[36:37], 0, s[4:5]
	s_mov_b32 s4, 0x4900000
	global_load_dwordx4 v[0:3], v33, s[20:21] offset:3072
	global_load_dwordx4 v[4:7], v33, s[22:23] offset:3072
	global_load_dwordx4 v[8:11], v33, s[22:23] offset:2048
	global_load_dwordx4 v[12:15], v33, s[20:21] offset:2048
	global_load_dwordx4 v[16:19], v33, s[22:23] offset:1024
	global_load_dwordx4 v[20:23], v33, s[20:21] offset:1024
	global_load_dwordx4 v[24:27], v33, s[22:23]
	global_load_dwordx4 v[28:31], v33, s[20:21]
	v_add_co_u32_e32 v36, vcc, s4, v36
	v_mbcnt_hi_u32_b32 v33, -1, v193
	s_nop 0
	v_addc_co_u32_e32 v37, vcc, 0, v37, vcc
	global_load_dwordx2 v[82:83], v[36:37], off
	global_load_dwordx2 v[80:81], v[38:39], off offset:512
	global_load_dwordx2 v[78:79], v[38:39], off offset:1024
	global_load_dwordx2 v[76:77], v[38:39], off offset:1536
	v_and_b32_e32 v35, 64, v33
	v_add_u32_e32 v35, 64, v35
	v_xor_b32_e32 v36, 1, v33
	v_cmp_lt_i32_e32 vcc, v36, v35
	s_add_i32 s10, s10, 8
	v_readlane_b32 s4, v248, 9
	v_cndmask_b32_e32 v36, v33, v36, vcc
	v_lshlrev_b32_e32 v84, 2, v36
	v_xor_b32_e32 v36, 2, v33
	v_cmp_lt_i32_e32 vcc, v36, v35
	s_mul_i32 s18, s92, s10
	v_readlane_b32 s5, v248, 10
	v_cndmask_b32_e32 v36, v33, v36, vcc
	v_lshlrev_b32_e32 v85, 2, v36
	v_xor_b32_e32 v36, 4, v33
	v_cmp_lt_i32_e32 vcc, v36, v35
	s_add_i32 s10, s96, s18
	s_mov_b32 s12, s4
	v_cndmask_b32_e32 v36, v33, v36, vcc
	v_lshlrev_b32_e32 v86, 2, v36
	v_xor_b32_e32 v36, 8, v33
	v_cmp_lt_i32_e32 vcc, v36, v35
	s_ashr_i32 s13, s4, 31
	v_writelane_b32 v248, s4, 9
	v_cndmask_b32_e32 v36, v33, v36, vcc
	v_lshlrev_b32_e32 v87, 2, v36
	v_xor_b32_e32 v36, 16, v33
	v_cmp_lt_i32_e32 vcc, v36, v35
	s_ashr_i32 s11, s10, 31
	v_writelane_b32 v248, s5, 10
	v_cndmask_b32_e32 v36, v33, v36, vcc
	v_lshlrev_b32_e32 v88, 2, v36
	v_xor_b32_e32 v36, 32, v33
	v_cmp_lt_i32_e32 vcc, v36, v35
	s_lshl_b64 s[4:5], s[12:13], 11
	s_lshl_b64 s[10:11], s[10:11], 11
	v_cndmask_b32_e32 v33, v33, v36, vcc
	v_and_b32_e32 v32, 63, v32
	s_add_u32 s8, s8, s10
	s_mov_b32 s24, -1
	v_lshlrev_b32_e32 v89, 2, v33
	v_lshlrev_b32_e32 v66, 3, v32
	v_mov_b32_e32 v67, v65
	s_addc_u32 s9, s9, s11
	s_movk_i32 s19, 0x4000
	v_lshlrev_b32_e32 v64, 2, v34
	s_mov_b64 s[10:11], 0x3000
	s_mov_b64 s[12:13], 0x4000
	s_mov_b32 s14, 0x3a800000
	s_mov_b32 s20, 0x800000
	s_mov_b32 s21, 0xc800000
	s_mov_b32 s22, 0x2800000
	s_mov_b32 s23, s96
	s_branch .LBB0_1075

.LBB0_1079:
	s_waitcnt vmcnt(0)
	s_barrier
	s_mov_b64 s[2:3], exec
	v_readlane_b32 s4, v248, 7
	v_readlane_b32 s5, v248, 8
	s_and_b64 s[4:5], s[2:3], s[4:5]
	s_mov_b64 exec, s[4:5]
	s_cbranch_execz .LBB0_1131
	v_readlane_b32 s4, v248, 4
	v_readlane_b32 s5, v248, 5
	v_readlane_b32 s8, v248, 6
	v_readlane_b32 s9, v249, 14
	v_readlane_b32 s10, v249, 15
	v_mov_b32_e32 v1, 1
	v_mov_b32_e32 v3, 0x3400
	s_nop 1
	s_lshl_b32 s8, s8, 8
	s_mul_i32 s9, s9, 9
	s_mul_i32 s10, s10, 9
	v_mov_b32_e32 v0, s8
	v_add_u32_e32 v2, 0x1000, v0
	v_add_u32_e32 v4, 0x2000, v0
	s_nop 1
	global_atomic_add v5, v2, v1, s[4:5] offset:1024 sc0
	s_waitcnt vmcnt(0)
	v_readfirstlane_b32 s11, v5
	s_nop 1
	s_add_u32 s11, s11, 1
	s_cmp_eq_u32 s11, s9
	s_cbranch_scc0 .Lhb8_follower
	buffer_wbl2 sc1
	s_waitcnt vmcnt(0)
	buffer_inv sc1
	global_atomic_add v5, v3, v1, s[4:5] sc0
	s_waitcnt vmcnt(0)
	v_readfirstlane_b32 s11, v5
	s_nop 1
	s_add_u32 s11, s11, 1
	s_cmp_ge_u32 s11, s10
	s_cbranch_scc1 .Lhb8_topdone
	s_movk_i32 s12, 0x4000

.Lhb8_fspin:
	global_load_dword v5, v4, s[4:5] offset:1024 sc1
	s_waitcnt vmcnt(0)
	v_readfirstlane_b32 s11, v5
	s_nop 1
	s_cmp_gt_u32 s11, 8
	s_cbranch_scc1 .Lhb8_fdone
	s_sleep 1
	s_sub_u32 s12, s12, 1
	s_cmp_lg_u32 s12, 0
	s_cbranch_scc1 .Lhb8_fspin
.Lhb8_fdone:
	s_waitcnt vmcnt(0)
.Lhb8_done:
.LBB0_1131:
	s_or_b64 exec, exec, s[2:3]
	s_waitcnt lgkmcnt(0)
	s_barrier
	v_mov_b32_e32 v0, v192
	s_load_dwordx2 s[4:5], s[0:1], 0xc0
	s_load_dwordx4 s[16:19], s[0:1], 0xb0
	v_mov_b32_e32 v8, v192
	s_cmpk_lt_i32 s96, 0x5ac
	s_cselect_b64 s[8:9], -1, 0
	s_cmpk_gt_i32 s96, 0x5ab
	v_readfirstlane_b32 s28, v8
	s_cbranch_scc1 .LBB0_1137
	s_ashr_i32 s2, s96, 31
	s_lshr_b32 s2, s2, 29
	s_add_i32 s10, s96, s2
	s_and_b32 s2, s10, -8
	s_sub_i32 s11, s96, s2
	s_cmp_gt_i32 s11, 3
	s_cbranch_scc0 .LBB0_1134
	s_mul_i32 s2, s11, 0xb5
	s_add_i32 s12, s2, 4
	s_cbranch_execz .LBB0_1135
	s_branch .LBB0_1136

.LBB0_1214:
	s_waitcnt vmcnt(0)
	s_barrier
	s_mov_b64 s[2:3], exec
	v_readlane_b32 s4, v248, 7
	v_readlane_b32 s5, v248, 8
	s_and_b64 s[4:5], s[2:3], s[4:5]
	s_mov_b64 exec, s[4:5]
	s_cbranch_execz .LBB0_1266
	v_readlane_b32 s4, v248, 4
	v_readlane_b32 s5, v248, 5
	v_readlane_b32 s8, v248, 6
	v_readlane_b32 s9, v249, 14
	v_readlane_b32 s10, v249, 15
	v_mov_b32_e32 v1, 1
	v_mov_b32_e32 v3, 0x3400
	s_nop 1
	s_lshl_b32 s8, s8, 8
	s_mul_i32 s9, s9, 10
	s_mul_i32 s10, s10, 10
	v_mov_b32_e32 v0, s8
	v_add_u32_e32 v2, 0x1000, v0
	v_add_u32_e32 v4, 0x2000, v0
	s_nop 1
	global_atomic_add v5, v2, v1, s[4:5] offset:1024 sc0
	s_waitcnt vmcnt(0)
	v_readfirstlane_b32 s11, v5
	s_nop 1
	s_add_u32 s11, s11, 1
	s_cmp_eq_u32 s11, s9
	s_cbranch_scc0 .Lhb9_follower
	buffer_wbl2 sc1
	s_waitcnt vmcnt(0)
	buffer_inv sc1
	global_atomic_add v5, v3, v1, s[4:5] sc0
	s_waitcnt vmcnt(0)
	v_readfirstlane_b32 s11, v5
	s_nop 1
	s_add_u32 s11, s11, 1
	s_cmp_ge_u32 s11, s10
	s_cbranch_scc1 .Lhb9_topdone
	s_movk_i32 s12, 0x4000

.Lhb9_fspin:
	global_load_dword v5, v4, s[4:5] offset:1024 sc1
	s_waitcnt vmcnt(0)
	v_readfirstlane_b32 s11, v5
	s_nop 1
	s_cmp_gt_u32 s11, 9
	s_cbranch_scc1 .Lhb9_fdone
	s_sleep 1
	s_sub_u32 s12, s12, 1
	s_cmp_lg_u32 s12, 0
	s_cbranch_scc1 .Lhb9_fspin
.Lhb9_fdone:
	s_waitcnt vmcnt(0)
.Lhb9_done:
.LBB0_1266:
	s_or_b64 exec, exec, s[2:3]
	s_waitcnt lgkmcnt(0)
	v_mov_b32_e32 v0, v192
	s_barrier
	s_load_dwordx2 s[2:3], s[0:1], 0xf0
	s_and_b64 vcc, exec, s[6:7]
	s_cbranch_vccnz .LBB0_1279
	s_lshr_b32 s4, s97, 29
	s_add_i32 s8, s96, s4
	s_and_b32 s4, s8, -8
	s_sub_i32 s9, s96, s4
	s_cmp_gt_i32 s9, -1
	s_cbranch_scc0 .LBB0_1269
	s_lshl_b32 s10, s9, 5
	s_cbranch_execz .LBB0_1270
	s_branch .LBB0_1271
